# P0 row loop: next-row loads as global_ loads waited with a counted vmcnt at the loop bottom instead of vmcnt(0) right after issue, on top of the epilogue rings
# baseline (speedup 1.0000x reference)
; __global__ void __launch_bounds__(NWAVES * 64, 2) mk_fwd(Args args) {
;     ...
;         {
;             f32x4 cur[4], nxt[4];
;             int m = gw;
;             if (m < T) { const f32x4* xr = (const f32x4*)(x + (size_t)m * DM) + lane;
; #pragma unroll
;                 for (int j = 0; j < 4; ++j) cur[j] = xr[64 * j]; }
; #pragma unroll 1
;             for (; m < T; m += NGW) {
;                 const int mn = m + NGW;
;                 if (mn < T) { const f32x4* xr = (const f32x4*)(x + (size_t)mn * DM) + lane;
; #pragma unroll
;                     for (int j = 0; j < 4; ++j) nxt[j] = xr[64 * j]; }
;     ...
;                 for (int j = 0; j < 4; ++j) cur[j] = nxt[j];
.LBB0_34:
	s_or_b64 exec, exec, s[10:11]
	s_cmp_lt_i32 s14, 0x8000
	v_mov_b32_e32 v19, 0
	s_waitcnt lgkmcnt(0)
	s_barrier
	s_cbranch_scc0 .LBB0_41
	v_mov_b32_e32 v177, v19
	s_ashr_i32 s15, s14, 31
	v_lshl_add_u64 v[22:23], s[4:5], 0, v[176:177]
	s_lshl_b64 s[4:5], s[14:15], 12
	v_lshrrev_b32_e32 v0, 1, v17
	s_add_u32 s4, s12, s4
	v_and_b32_e32 v18, 28, v0
	s_addc_u32 s5, s13, s5
	v_lshl_add_u64 v[0:1], s[6:7], 0, v[18:19]
	v_lshl_add_u32 v140, v20, 4, 0
	v_lshl_add_u64 v[20:21], s[4:5], 0, v[176:177]
	flat_load_dword v190, v[0:1]
	s_nop 0
	flat_load_dwordx4 v[0:3], v[22:23] offset:3072
	flat_load_dwordx4 v[4:7], v[22:23] offset:2048
	flat_load_dwordx4 v[8:11], v[22:23] offset:1024
	flat_load_dwordx4 v[12:15], v[22:23]
	flat_load_dwordx4 v[172:175], v[20:21]
	flat_load_dwordx4 v[168:171], v[20:21] offset:1024
	flat_load_dwordx4 v[164:167], v[20:21] offset:2048
	flat_load_dwordx4 v[160:163], v[20:21] offset:3072
	v_mbcnt_lo_u32_b32 v20, -1, 0
	v_mbcnt_hi_u32_b32 v20, -1, v20
	v_and_b32_e32 v21, 64, v20
	v_add_u32_e32 v21, 64, v21
	v_xor_b32_e32 v22, 1, v20
	v_cmp_lt_i32_e32 vcc, v22, v21
	s_lshl_b64 s[28:29], s[14:15], 5
	s_add_u32 s26, s26, s28
	v_cndmask_b32_e32 v22, v20, v22, vcc
	v_lshlrev_b32_e32 v191, 2, v22
	v_xor_b32_e32 v22, 2, v20
	v_cmp_lt_i32_e32 vcc, v22, v21
	s_addc_u32 s27, s27, s29
	v_cmp_eq_u32_e64 s[10:11], 0, v16
	v_cndmask_b32_e32 v22, v20, v22, vcc
	v_lshlrev_b32_e32 v192, 2, v22
	v_xor_b32_e32 v22, 4, v20
	v_cmp_lt_i32_e32 vcc, v22, v21
	s_ashr_i32 s39, s38, 31
	s_lshl_b64 s[28:29], s[14:15], 11
	v_cndmask_b32_e32 v22, v20, v22, vcc
	v_lshlrev_b32_e32 v193, 2, v22
	v_xor_b32_e32 v22, 8, v20
	v_cmp_lt_i32_e32 vcc, v22, v21
	v_mov_b32_e32 v179, v19
	s_mov_b32 s3, 0xf800000
	v_cndmask_b32_e32 v22, v20, v22, vcc
	v_lshlrev_b32_e32 v194, 2, v22
	v_xor_b32_e32 v22, 16, v20
	v_cmp_lt_i32_e32 vcc, v22, v21
	s_mov_b32 s15, 0xbfb8aa3b
	s_mov_b32 s33, 0xb2a5705f
	v_cndmask_b32_e32 v22, v20, v22, vcc
	v_lshlrev_b32_e32 v195, 2, v22
	v_xor_b32_e32 v22, 32, v20
	v_cmp_lt_i32_e32 vcc, v22, v21
	s_mov_b32 s34, 0x42ce8ed0
	s_mov_b32 s35, 0xc2b17218
	v_cndmask_b32_e32 v20, v20, v22, vcc
	v_lshlrev_b32_e32 v196, 2, v20
	v_and_b32_e32 v20, 32, v17
	v_cmp_eq_u32_e64 s[4:5], 0, v20
	v_and_b32_e32 v20, 16, v17
	v_and_b32_e32 v17, 8, v17
	v_cmp_eq_u32_e64 s[8:9], 0, v17
	v_lshl_add_u64 v[16:17], s[26:27], 0, v[18:19]
	s_mov_b64 s[26:27], 0x2000000
	v_lshl_add_u64 v[180:181], v[16:17], 0, s[26:27]
	s_lshl_b64 s[26:27], s[38:39], 5
	s_add_u32 s22, s22, s28
	s_addc_u32 s23, s23, s29
	v_lshl_add_u64 v[16:17], s[22:23], 0, v[178:179]
	s_mov_b64 s[22:23], 0x4000000
	v_lshl_add_u64 v[182:183], v[16:17], 0, s[22:23]
	v_cmp_eq_u32_e64 s[6:7], 0, v20
	ds_read_b128 v[16:19], v140 offset:31744
	ds_read_b128 v[20:23], v140 offset:30720
	ds_read_b128 v[24:27], v140 offset:29696
	ds_read_b128 v[28:31], v140 offset:28672
	ds_read_b128 v[32:35], v140 offset:27648
	ds_read_b128 v[36:39], v140 offset:26624
	ds_read_b128 v[40:43], v140 offset:25600
	ds_read_b128 v[44:47], v140 offset:24576
	ds_read_b128 v[48:51], v140 offset:23552
	ds_read_b128 v[52:55], v140 offset:22528
	ds_read_b128 v[56:59], v140 offset:21504
	ds_read_b128 v[60:63], v140 offset:20480
	ds_read_b128 v[64:67], v140 offset:19456
	ds_read_b128 v[68:71], v140 offset:18432
	ds_read_b128 v[72:75], v140 offset:17408
	ds_read_b128 v[76:79], v140 offset:16384
	ds_read_b128 v[80:83], v140 offset:15360
	ds_read_b128 v[84:87], v140 offset:14336
	ds_read_b128 v[88:91], v140 offset:13312
	ds_read_b128 v[92:95], v140 offset:12288
	ds_read_b128 v[96:99], v140 offset:11264
	ds_read_b128 v[100:103], v140 offset:10240
	ds_read_b128 v[104:107], v140 offset:9216
	ds_read_b128 v[108:111], v140 offset:8192
	ds_read_b128 v[112:115], v140 offset:7168
	ds_read_b128 v[116:119], v140 offset:6144
	ds_read_b128 v[120:123], v140 offset:5120
	ds_read_b128 v[124:127], v140 offset:4096
	ds_read_b128 v[128:131], v140 offset:3072
	ds_read_b128 v[132:135], v140 offset:2048
	ds_read_b128 v[136:139], v140 offset:1024
	ds_read_b128 v[140:143], v140
	s_add_i32 s28, s14, s38
	s_ashr_i32 s29, s28, 31
	s_lshl_b64 s[22:23], s[38:39], 11
	s_lshl_b64 s[28:29], s[28:29], 12
	s_add_u32 s12, s12, s28
	s_addc_u32 s13, s13, s29
	v_lshl_add_u64 v[184:185], s[12:13], 0, v[176:177]
	s_lshl_b64 s[28:29], s[38:39], 12
	v_mov_b32_e32 v177, 0x358637bd
	v_mov_b32_e32 v179, 0x260
	s_mov_b32 s36, 0x7f800000
	s_mov_b32 s37, 0x3f2aaaab
	v_mov_b32_e32 v197, 0x3ecc95a3
	s_mov_b32 s39, 0x3f317218
	s_mov_b32 s42, 0x33800000
	v_mov_b32_e32 v198, 0x7f800000
	v_mov_b32_e32 v186, 0x3f317218
	s_mov_b32 s43, s14
	s_waitcnt vmcnt(0) lgkmcnt(0)
	s_branch .LBB0_37
.LBB0_36:
	s_or_b64 exec, exec, s[12:13]
	s_waitcnt vmcnt(5)
	v_mov_b64_e32 v[174:175], v[146:147]
	v_mov_b64_e32 v[170:171], v[150:151]
	v_mov_b64_e32 v[166:167], v[154:155]
	s_waitcnt lgkmcnt(0)
	v_mov_b64_e32 v[162:163], v[158:159]
	v_lshl_add_u64 v[180:181], v[180:181], 0, s[26:27]
	v_lshl_add_u64 v[182:183], v[182:183], 0, s[22:23]
	v_lshl_add_u64 v[184:185], v[184:185], 0, s[28:29]
	s_andn2_b64 vcc, exec, s[30:31]
	v_mov_b64_e32 v[172:173], v[144:145]
	v_mov_b64_e32 v[168:169], v[148:149]
	v_mov_b64_e32 v[164:165], v[152:153]
	v_mov_b64_e32 v[160:161], v[156:157]
	s_cbranch_vccz .LBB0_41
.LBB0_37:
	s_add_i32 s43, s43, s38
	s_cmpk_gt_i32 s43, 0x7fff
	s_cselect_b64 s[30:31], -1, 0
	s_and_b64 vcc, exec, s[30:31]
	s_cbranch_vccnz .LBB0_39
	global_load_dwordx4 v[144:147], v[184:185], off
	global_load_dwordx4 v[148:151], v[184:185], off offset:1024
	global_load_dwordx4 v[152:155], v[184:185], off offset:2048
	global_load_dwordx4 v[156:159], v[184:185], off offset:3072
; __global__ void __launch_bounds__(NWAVES * 64, 2) mk_fwd(Args args) {
;     ...
;                 float s = 0.f;
; #pragma unroll
;                 for (int j = 0; j < 4; ++j) s += (cur[j][0] * cur[j][0] + cur[j][1] * cur[j][1]) + (cur[j][2] * cur[j][2] + cur[j][3] * cur[j][3]);
;                 float z[8];
; #pragma unroll
;                 for (int h = 0; h < 8; ++h) z[h] = 0.f;
; #pragma unroll
;                 for (int j = 0; j < 4; ++j) { cur[j] = cur[j] * gg[j];
; #pragma unroll
;                     for (int h = 0; h < 8; ++h) z[h] += (cur[j][0] * wfr[h][j][0] + cur[j][1] * wfr[h][j][1]) + (cur[j][2] * wfr[h][j][2] + cur[j][3] * wfr[h][j][3]); }
.LBB0_39:
	s_waitcnt lgkmcnt(0)
	v_pk_mul_f32 v[188:189], v[170:171], v[170:171]
	v_pk_mul_f32 v[200:201], v[168:169], v[168:169]
	v_mul_f32_e32 v187, v160, v160
	v_pk_mov_b32 v[202:203], v[200:201], v[188:189] op_sel:[1,0]
	v_mov_b32_e32 v201, v189
	v_pk_add_f32 v[188:189], v[202:203], v[200:201]
	v_pk_mul_f32 v[200:201], v[174:175], v[174:175]
	v_pk_mul_f32 v[202:203], v[172:173], v[172:173]
	v_mul_f32_e32 v199, v161, v161
	v_pk_mov_b32 v[204:205], v[202:203], v[200:201] op_sel:[1,0]
	v_mov_b32_e32 v203, v201
	v_pk_add_f32 v[200:201], v[204:205], v[202:203]
	v_pk_add_f32 v[188:189], v[188:189], v[188:189] op_sel:[0,1] op_sel_hi:[1,0]
	v_pk_add_f32 v[200:201], v[200:201], v[200:201] op_sel:[0,1] op_sel_hi:[1,0]
	v_pk_mul_f32 v[174:175], v[174:175], v[14:15]
	v_pk_mul_f32 v[172:173], v[172:173], v[12:13]
	v_mov_b32_e32 v201, v187
	v_mov_b32_e32 v189, v199
	v_mul_f32_e32 v187, v173, v141
	v_mul_f32_e32 v199, v175, v143
	v_fmac_f32_e32 v187, v172, v140
	v_fmac_f32_e32 v199, v174, v142
	v_mul_f32_e32 v202, v165, v165
	v_mul_f32_e32 v204, v167, v167
	v_pk_add_f32 v[188:189], v[200:201], v[188:189]
	v_add_f32_e32 v187, v187, v199
	v_mul_f32_e32 v199, v173, v125
	v_mul_f32_e32 v200, v175, v127
	v_mul_f32_e32 v206, v162, v162
	v_mul_f32_e32 v207, v163, v163
	v_pk_fma_f32 v[202:203], v[164:165], v[164:165], v[202:203] op_sel_hi:[1,1,0]
	v_pk_fma_f32 v[204:205], v[166:167], v[166:167], v[204:205] op_sel_hi:[1,1,0]
	v_fmac_f32_e32 v199, v172, v124
	v_fmac_f32_e32 v200, v174, v126
	v_mov_b32_e32 v203, v206
	v_mov_b32_e32 v205, v207
	v_add_f32_e32 v199, v199, v200
	v_mul_f32_e32 v200, v173, v109
	v_mul_f32_e32 v201, v175, v111
	v_pk_add_f32 v[202:203], v[202:203], v[204:205]
	v_fmac_f32_e32 v200, v172, v108
	v_fmac_f32_e32 v201, v174, v110
	v_pk_add_f32 v[188:189], v[188:189], v[202:203]
	v_add_f32_e32 v200, v200, v201
	v_mul_f32_e32 v201, v173, v93
	v_mul_f32_e32 v202, v175, v95
	v_fmac_f32_e32 v201, v172, v92
	v_fmac_f32_e32 v202, v174, v94
	v_add_f32_e32 v201, v201, v202
	v_mul_f32_e32 v202, v173, v77
	v_mul_f32_e32 v203, v175, v79
	v_fmac_f32_e32 v202, v172, v76
	v_fmac_f32_e32 v203, v174, v78
	v_add_f32_e32 v202, v202, v203
	v_mul_f32_e32 v203, v173, v61
	v_mul_f32_e32 v204, v175, v63
	v_fmac_f32_e32 v203, v172, v60
	v_fmac_f32_e32 v204, v174, v62
	v_add_f32_e32 v203, v203, v204
	v_mul_f32_e32 v204, v173, v45
	v_mul_f32_e32 v205, v175, v47
	v_fmac_f32_e32 v204, v172, v44
	v_fmac_f32_e32 v205, v174, v46
	v_add_f32_e32 v204, v204, v205
	v_mul_f32_e32 v205, v173, v29
	v_mul_f32_e32 v206, v175, v31
	v_fmac_f32_e32 v205, v172, v28
	v_fmac_f32_e32 v206, v174, v30
	v_pk_mul_f32 v[170:171], v[170:171], v[10:11]
	v_pk_mul_f32 v[168:169], v[168:169], v[8:9]
	v_add_f32_e32 v205, v205, v206
	v_mul_f32_e32 v206, v169, v137
	v_mul_f32_e32 v207, v171, v139
	v_fmac_f32_e32 v206, v168, v136
	v_fmac_f32_e32 v207, v170, v138
	v_add_f32_e32 v187, 0, v187
	v_add_f32_e32 v206, v206, v207
	v_add_f32_e32 v187, v187, v206
	v_mul_f32_e32 v206, v169, v121
	v_mul_f32_e32 v207, v171, v123
	v_fmac_f32_e32 v206, v168, v120
	v_fmac_f32_e32 v207, v170, v122
	v_add_f32_e32 v199, 0, v199
	v_add_f32_e32 v206, v206, v207
	v_add_f32_e32 v199, v199, v206
	v_mul_f32_e32 v206, v169, v105
	v_mul_f32_e32 v207, v171, v107
	v_fmac_f32_e32 v206, v168, v104
	v_fmac_f32_e32 v207, v170, v106
	v_add_f32_e32 v200, 0, v200
	v_add_f32_e32 v206, v206, v207
	v_add_f32_e32 v200, v200, v206
	v_mul_f32_e32 v206, v169, v89
	v_mul_f32_e32 v207, v171, v91
	v_fmac_f32_e32 v206, v168, v88
	v_fmac_f32_e32 v207, v170, v90
	v_add_f32_e32 v201, 0, v201
	v_add_f32_e32 v206, v206, v207
	v_add_f32_e32 v201, v201, v206
	v_mul_f32_e32 v206, v169, v73
	v_mul_f32_e32 v207, v171, v75
	v_fmac_f32_e32 v206, v168, v72
	v_fmac_f32_e32 v207, v170, v74
	v_add_f32_e32 v202, 0, v202
	v_add_f32_e32 v206, v206, v207
	v_add_f32_e32 v202, v202, v206
	v_mul_f32_e32 v206, v169, v57
	v_mul_f32_e32 v207, v171, v59
	v_fmac_f32_e32 v206, v168, v56
	v_fmac_f32_e32 v207, v170, v58
	v_add_f32_e32 v203, 0, v203
	v_add_f32_e32 v206, v206, v207
	v_add_f32_e32 v203, v203, v206
	v_mul_f32_e32 v206, v169, v41
	v_mul_f32_e32 v207, v171, v43
	v_fmac_f32_e32 v206, v168, v40
	v_fmac_f32_e32 v207, v170, v42
	v_add_f32_e32 v204, 0, v204
	v_add_f32_e32 v206, v206, v207
	v_add_f32_e32 v204, v204, v206
	v_mul_f32_e32 v206, v169, v25
	v_mul_f32_e32 v207, v171, v27
	v_fmac_f32_e32 v206, v168, v24
	v_fmac_f32_e32 v207, v170, v26
	v_add_f32_e32 v205, 0, v205
	v_add_f32_e32 v206, v206, v207
	v_pk_mul_f32 v[166:167], v[166:167], v[6:7]
	v_pk_mul_f32 v[164:165], v[164:165], v[4:5]
	v_add_f32_e32 v205, v205, v206
	v_mul_f32_e32 v206, v165, v133
	v_mul_f32_e32 v207, v167, v135
	v_fmac_f32_e32 v206, v164, v132
	v_fmac_f32_e32 v207, v166, v134
	v_add_f32_e32 v206, v206, v207
	v_add_f32_e32 v187, v187, v206
	v_mul_f32_e32 v206, v165, v117
	v_mul_f32_e32 v207, v167, v119
	v_fmac_f32_e32 v206, v164, v116
	v_fmac_f32_e32 v207, v166, v118
	v_add_f32_e32 v206, v206, v207
	v_add_f32_e32 v199, v199, v206
	v_mul_f32_e32 v206, v165, v101
	v_mul_f32_e32 v207, v167, v103
	v_fmac_f32_e32 v206, v164, v100
	v_fmac_f32_e32 v207, v166, v102
	v_add_f32_e32 v206, v206, v207
	v_add_f32_e32 v206, v200, v206
	v_mul_f32_e32 v200, v165, v85
	v_mul_f32_e32 v207, v167, v87
	v_fmac_f32_e32 v200, v164, v84
	v_fmac_f32_e32 v207, v166, v86
	v_add_f32_e32 v200, v200, v207
	v_add_f32_e32 v207, v201, v200
	v_mul_f32_e32 v200, v165, v69
	v_mul_f32_e32 v201, v167, v71
	v_fmac_f32_e32 v200, v164, v68
	v_fmac_f32_e32 v201, v166, v70
	v_add_f32_e32 v200, v200, v201
	v_add_f32_e32 v202, v202, v200
	v_mul_f32_e32 v200, v165, v53
	v_mul_f32_e32 v201, v167, v55
	v_fmac_f32_e32 v200, v164, v52
	v_fmac_f32_e32 v201, v166, v54
	v_add_f32_e32 v200, v200, v201
	v_add_f32_e32 v203, v203, v200
	v_mul_f32_e32 v200, v165, v37
	v_mul_f32_e32 v201, v167, v39
	v_fmac_f32_e32 v200, v164, v36
	v_fmac_f32_e32 v201, v166, v38
	v_add_f32_e32 v200, v200, v201
	v_add_f32_e32 v204, v204, v200
	v_mul_f32_e32 v200, v165, v21
	v_mul_f32_e32 v201, v167, v23
	v_fmac_f32_e32 v200, v164, v20
	v_fmac_f32_e32 v201, v166, v22
	v_add_f32_e32 v200, v200, v201
	v_add_f32_e32 v205, v205, v200
	v_pk_mul_f32 v[162:163], v[162:163], v[2:3]
	v_pk_mul_f32 v[200:201], v[160:161], v[0:1]
	v_mul_f32_e32 v161, v163, v131
	v_mul_f32_e32 v160, v201, v129
	v_fmac_f32_e32 v160, v200, v128
	v_fmac_f32_e32 v161, v162, v130
	v_add_f32_e32 v160, v160, v161
	v_add_f32_e32 v161, v187, v160
	v_mul_f32_e32 v160, v201, v113
	v_mul_f32_e32 v187, v163, v115
	v_fmac_f32_e32 v160, v200, v112
	v_fmac_f32_e32 v187, v162, v114
	v_add_f32_e32 v160, v160, v187
	v_add_f32_e32 v187, v199, v160
	v_mul_f32_e32 v160, v201, v97
	v_mul_f32_e32 v199, v163, v99
	v_fmac_f32_e32 v160, v200, v96
	v_fmac_f32_e32 v199, v162, v98
	v_add_f32_e32 v160, v160, v199
	v_add_f32_e32 v199, v206, v160
	v_add_f32_e32 v160, v188, v189
	ds_bpermute_b32 v188, v191, v160
	v_mul_f32_e32 v189, v201, v81
	v_mul_f32_e32 v206, v163, v83
	v_fmac_f32_e32 v189, v200, v80
	v_fmac_f32_e32 v206, v162, v82
	s_waitcnt lgkmcnt(0)
; __device__ __forceinline__ unsigned pk2(float lo, float hi) { return pg8::cvt_pk_bf16(lo, hi); }
; __global__ void __launch_bounds__(NWAVES * 64, 2) mk_fwd(Args args) {
;     ...
;                 for (int j = 0; j < 4; ++j) { cur[j] = cur[j] * gg[j];
; #pragma unroll
;                     for (int h = 0; h < 8; ++h) z[h] += (cur[j][0] * wfr[h][j][0] + cur[j][1] * wfr[h][j][1]) + (cur[j][2] * wfr[h][j][2] + cur[j][3] * wfr[h][j][3]); }
;                 const float rs = 1.0f / sqrtf(wave_sum(s) * (1.f / DM) + EPS);
;                 unsigned long long* o8 = (unsigned long long*)(XN + (size_t)m * DM) + lane;
; #pragma unroll
;                 for (int j = 0; j < 4; ++j) { const f32x4 v = cur[j] * rs; o8[64 * j] = (unsigned long long)pk2(v[0], v[1]) | ((unsigned long long)pk2(v[2], v[3]) << 32); }
;                 float s4[4], s2[2], s1;
; #pragma unroll
;                 for (int i = 0; i < 4; ++i) { const float send = (lane & 32) ? z[i] : z[4 + i], keep = (lane & 32) ? z[4 + i] : z[i]; s4[i] = keep + __shfl_xor(send, 32); }
; #pragma unroll
;                 for (int i = 0; i < 2; ++i) { const float send = (lane & 16) ? s4[i] : s4[2 + i], keep = (lane & 16) ? s4[2 + i] : s4[i]; s2[i] = keep + __shfl_xor(send, 16); }
;                 { const float send = (lane & 8) ? s2[0] : s2[1], keep = (lane & 8) ? s2[1] : s2[0]; s1 = keep + __shfl_xor(send, 8); }
;                 s1 += __shfl_xor(s1, 4); s1 += __shfl_xor(s1, 2); s1 += __shfl_xor(s1, 1);
	v_add_f32_e32 v160, v160, v188
	ds_bpermute_b32 v188, v192, v160
	v_add_f32_e32 v189, v189, v206
	v_add_f32_e32 v189, v207, v189
	v_mul_f32_e32 v206, v201, v65
	v_mul_f32_e32 v207, v163, v67
	s_waitcnt lgkmcnt(0)
	v_add_f32_e32 v160, v160, v188
	ds_bpermute_b32 v188, v193, v160
	v_fmac_f32_e32 v206, v200, v64
	v_fmac_f32_e32 v207, v162, v66
	v_add_f32_e32 v206, v206, v207
	v_add_f32_e32 v202, v202, v206
	s_waitcnt lgkmcnt(0)
	v_add_f32_e32 v160, v160, v188
	ds_bpermute_b32 v188, v194, v160
	v_mul_f32_e32 v206, v201, v49
	v_mul_f32_e32 v207, v163, v51
	v_fmac_f32_e32 v206, v200, v48
	v_fmac_f32_e32 v207, v162, v50
	s_waitcnt lgkmcnt(0)
	v_add_f32_e32 v160, v160, v188
	ds_bpermute_b32 v188, v195, v160
	v_add_f32_e32 v206, v206, v207
	v_add_f32_e32 v203, v203, v206
	v_mul_f32_e32 v206, v201, v33
	v_mul_f32_e32 v207, v163, v35
	s_waitcnt lgkmcnt(0)
	v_add_f32_e32 v160, v160, v188
	ds_bpermute_b32 v188, v196, v160
	v_fmac_f32_e32 v206, v200, v32
	v_fmac_f32_e32 v207, v162, v34
	v_add_f32_e32 v206, v206, v207
	v_add_f32_e32 v204, v204, v206
	s_waitcnt lgkmcnt(0)
	v_add_f32_e32 v160, v160, v188
	v_fmamk_f32 v160, v160, 0x3a800000, v177
	v_mul_f32_e32 v188, 0x4f800000, v160
	v_cmp_gt_f32_e32 vcc, s3, v160
	v_mul_f32_e32 v206, v201, v17
	v_mul_f32_e32 v207, v163, v19
	v_cndmask_b32_e32 v160, v160, v188, vcc
	v_sqrt_f32_e32 v188, v160
	v_fmac_f32_e32 v206, v200, v16
	v_fmac_f32_e32 v207, v162, v18
	v_add_f32_e32 v206, v206, v207
	v_add_u32_e32 v208, -1, v188
	v_fma_f32 v209, -v208, v188, v160
	v_cmp_ge_f32_e64 s[12:13], 0, v209
	v_add_u32_e32 v209, 1, v188
	v_add_f32_e32 v205, v205, v206
	v_cndmask_b32_e64 v208, v188, v208, s[12:13]
	v_fma_f32 v188, -v209, v188, v160
	v_cmp_lt_f32_e64 s[12:13], 0, v188
	s_nop 1
	v_cndmask_b32_e64 v188, v208, v209, s[12:13]
	v_mul_f32_e32 v208, 0x37800000, v188
	v_cndmask_b32_e32 v188, v188, v208, vcc
	v_cmp_class_f32_e32 vcc, v160, v179
	s_nop 1
	v_cndmask_b32_e32 v160, v188, v160, vcc
	v_div_scale_f32 v188, s[12:13], v160, v160, 1.0
	v_rcp_f32_e32 v208, v188
	s_nop 0
	v_fma_f32 v206, -v188, v208, 1.0
	v_fmac_f32_e32 v208, v206, v208
	v_div_scale_f32 v206, vcc, 1.0, v160, 1.0
	v_mul_f32_e32 v207, v206, v208
	v_fma_f32 v209, -v188, v207, v206
	v_fmac_f32_e32 v207, v209, v208
	v_fma_f32 v188, -v188, v207, v206
	v_div_fmas_f32 v188, v188, v208, v207
	v_div_fixup_f32 v160, v188, v160, 1.0
	v_cndmask_b32_e64 v188, v161, v202, s[4:5]
	ds_bpermute_b32 v188, v196, v188
	v_pk_mul_f32 v[174:175], v[160:161], v[174:175] op_sel_hi:[0,1]
	v_pk_mul_f32 v[172:173], v[160:161], v[172:173] op_sel_hi:[0,1]
	v_cvt_pk_bf16_f32 v172, v172, v173
	v_cvt_pk_bf16_f32 v173, v174, v175
	v_cndmask_b32_e64 v174, v187, v203, s[4:5]
	v_cndmask_b32_e64 v161, v202, v161, s[4:5]
	v_cndmask_b32_e64 v175, v203, v187, s[4:5]
	ds_bpermute_b32 v174, v196, v174
	v_cndmask_b32_e64 v187, v199, v204, s[4:5]
	s_waitcnt lgkmcnt(1)
	v_add_f32_e32 v161, v161, v188
	ds_bpermute_b32 v187, v196, v187
	v_cndmask_b32_e64 v188, v189, v205, s[4:5]
	ds_bpermute_b32 v188, v196, v188
	s_waitcnt lgkmcnt(2)
	v_add_f32_e32 v174, v175, v174
	v_cndmask_b32_e64 v175, v204, v199, s[4:5]
	s_waitcnt lgkmcnt(1)
	v_add_f32_e32 v175, v175, v187
	v_cndmask_b32_e64 v187, v205, v189, s[4:5]
	s_waitcnt lgkmcnt(0)
	v_add_f32_e32 v187, v187, v188
	v_cndmask_b32_e64 v188, v161, v175, s[6:7]
	v_cndmask_b32_e64 v189, v174, v187, s[6:7]
	ds_bpermute_b32 v188, v195, v188
	ds_bpermute_b32 v189, v195, v189
	global_store_dwordx2 v[182:183], v[172:173], off
	v_cndmask_b32_e64 v161, v175, v161, s[6:7]
	v_cndmask_b32_e64 v172, v187, v174, s[6:7]
	s_waitcnt lgkmcnt(0)
	v_add_f32_e32 v161, v161, v188
	v_add_f32_e32 v172, v172, v189
	v_cndmask_b32_e64 v173, v161, v172, s[8:9]
	ds_bpermute_b32 v173, v194, v173
	v_pk_mul_f32 v[170:171], v[160:161], v[170:171] op_sel_hi:[0,1]
	v_pk_mul_f32 v[168:169], v[160:161], v[168:169] op_sel_hi:[0,1]
	v_cndmask_b32_e64 v161, v172, v161, s[8:9]
	v_cvt_pk_bf16_f32 v168, v168, v169
	s_waitcnt lgkmcnt(0)
	v_add_f32_e32 v161, v161, v173
	ds_bpermute_b32 v172, v193, v161
	v_pk_mul_f32 v[166:167], v[160:161], v[166:167] op_sel_hi:[0,1]
	v_pk_mul_f32 v[164:165], v[160:161], v[164:165] op_sel_hi:[0,1]
	v_cvt_pk_bf16_f32 v169, v170, v171
	global_store_dwordx2 v[182:183], v[168:169], off offset:512
	s_waitcnt lgkmcnt(0)
	v_add_f32_e32 v161, v161, v172
	ds_bpermute_b32 v168, v192, v161
	v_cvt_pk_bf16_f32 v164, v164, v165
	v_cvt_pk_bf16_f32 v165, v166, v167
	global_store_dwordx2 v[182:183], v[164:165], off offset:1024
	v_pk_mul_f32 v[164:165], v[160:161], v[162:163] op_sel_hi:[0,1]
	s_waitcnt lgkmcnt(0)
	v_add_f32_e32 v161, v161, v168
	ds_bpermute_b32 v162, v191, v161
	v_pk_mul_f32 v[166:167], v[160:161], v[200:201] op_sel_hi:[0,1]
	v_cvt_pk_bf16_f32 v166, v166, v167
	v_cvt_pk_bf16_f32 v167, v164, v165
	global_store_dwordx2 v[182:183], v[166:167], off offset:1536
	s_and_saveexec_b64 s[12:13], s[10:11]
	s_cbranch_execz .LBB0_36
; __global__ void __launch_bounds__(NWAVES * 64, 2) mk_fwd(Args args) {
;     ...
;                 s1 += __shfl_xor(s1, 4); s1 += __shfl_xor(s1, 2); s1 += __shfl_xor(s1, 1);
;                 if ((lane & 7) == 0) { const float zz = s1 * rs + bfl; LOGF[(size_t)m * 8 + hsel] = fminf(zz, 0.f) - log1pf(expf(-fabsf(zz))); }
	s_waitcnt lgkmcnt(0)
	v_add_f32_e32 v161, v161, v162
	v_fma_f32 v160, v160, v161, v190
	v_mul_f32_e64 v161, |v160|, s15
	v_fma_f32 v162, |v160|, s15, -v161
	v_rndne_f32_e32 v163, v161
	v_fma_f32 v162, |v160|, s33, v162
	v_sub_f32_e32 v161, v161, v163
	v_add_f32_e32 v161, v161, v162
	v_exp_f32_e32 v161, v161
	v_cvt_i32_f32_e32 v162, v163
	v_cmp_ngt_f32_e64 vcc, |v160|, s34
	v_min_f32_e32 v174, 0, v160
	v_ldexp_f32 v161, v161, v162
	v_cndmask_b32_e32 v161, 0, v161, vcc
	v_cmp_nlt_f32_e64 vcc, |v160|, s35
	s_nop 1
	v_cndmask_b32_e32 v175, v198, v161, vcc
	v_add_f32_e32 v162, 1.0, v175
	v_add_f32_e32 v160, -1.0, v162
	v_sub_f32_e32 v161, v160, v162
	v_add_f32_e32 v161, 1.0, v161
	v_sub_f32_e32 v160, v175, v160
	v_add_f32_e32 v163, v160, v161
	v_frexp_mant_f32_e32 v164, v162
	v_cvt_f64_f32_e32 v[160:161], v162
	v_frexp_exp_i32_f64_e32 v160, v[160:161]
	v_cmp_gt_f32_e32 vcc, s37, v164
	s_nop 1
	v_subbrev_co_u32_e32 v168, vcc, 0, v160, vcc
	v_sub_u32_e32 v160, 0, v168
	v_ldexp_f32 v161, v162, v160
	v_add_f32_e32 v162, -1.0, v161
	v_add_f32_e32 v164, 1.0, v161
	v_ldexp_f32 v160, v163, v160
	v_add_f32_e32 v163, 1.0, v162
	v_add_f32_e32 v165, -1.0, v164
	v_sub_f32_e32 v163, v161, v163
	v_sub_f32_e32 v161, v161, v165
	v_add_f32_e32 v163, v160, v163
	v_add_f32_e32 v160, v160, v161
	v_add_f32_e32 v169, v164, v160
	v_rcp_f32_e32 v171, v169
	v_sub_f32_e32 v161, v164, v169
	v_add_f32_e32 v170, v160, v161
	v_add_f32_e32 v161, v162, v163
	v_mul_f32_e32 v173, v161, v171
	v_sub_f32_e32 v160, v162, v161
	v_mul_f32_e32 v162, v169, v173
	v_fma_f32 v164, v173, v169, -v162
	v_fmac_f32_e32 v164, v173, v170
	v_add_f32_e32 v172, v163, v160
	v_add_f32_e32 v160, v162, v164
	v_sub_f32_e32 v163, v161, v160
	v_pk_add_f32 v[166:167], v[160:161], v[162:163] neg_lo:[0,1] neg_hi:[0,1]
	v_mov_b32_e32 v165, v160
	v_pk_add_f32 v[160:161], v[166:167], v[164:165] neg_lo:[0,1] neg_hi:[0,1]
	v_cmp_neq_f32_e32 vcc, s36, v175
	v_add_f32_e32 v161, v172, v161
	v_add_f32_e32 v160, v160, v161
	v_add_f32_e32 v161, v163, v160
	v_mul_f32_e32 v172, v171, v161
	v_mul_f32_e32 v162, v169, v172
	v_fma_f32 v164, v172, v169, -v162
	v_fmac_f32_e32 v164, v172, v170
	v_sub_f32_e32 v163, v163, v161
	v_add_f32_e32 v169, v160, v163
	v_add_f32_e32 v160, v162, v164
	v_sub_f32_e32 v163, v161, v160
	v_pk_add_f32 v[166:167], v[160:161], v[162:163] neg_lo:[0,1] neg_hi:[0,1]
	v_mov_b32_e32 v165, v160
	v_pk_add_f32 v[160:161], v[166:167], v[164:165] neg_lo:[0,1] neg_hi:[0,1]
	s_nop 0
	v_add_f32_e32 v161, v169, v161
	v_add_f32_e32 v160, v160, v161
	v_add_f32_e32 v161, v173, v172
	v_add_f32_e32 v160, v163, v160
	v_sub_f32_e32 v162, v161, v173
	v_mul_f32_e32 v160, v171, v160
	v_sub_f32_e32 v162, v172, v162
	v_add_f32_e32 v162, v162, v160
	v_add_f32_e32 v164, v161, v162
	v_mul_f32_e32 v165, v164, v164
	v_fmamk_f32 v160, v165, 0x3e9b6dac, v197
	v_fmaak_f32 v187, v165, v160, 0x3f2aaada
	v_cvt_f32_i32_e32 v160, v168
	v_sub_f32_e32 v161, v164, v161
	v_sub_f32_e32 v161, v162, v161
	v_ldexp_f32 v166, v161, 1
	v_mul_f32_e32 v161, v164, v165
	v_ldexp_f32 v163, v164, 1
	v_pk_mul_f32 v[164:165], v[160:161], v[186:187]
	s_nop 0
	v_fma_f32 v162, v160, s39, -v164
	v_fmac_f32_e32 v162, 0xb102e308, v160
	v_pk_add_f32 v[160:161], v[164:165], v[162:163]
	s_nop 0
	v_sub_f32_e32 v163, v161, v163
	v_sub_f32_e32 v163, v165, v163
	v_add_f32_e32 v167, v166, v163
	v_mov_b32_e32 v166, v164
	v_pk_add_f32 v[164:165], v[160:161], v[164:165] neg_lo:[0,1] neg_hi:[0,1]
	v_pk_add_f32 v[168:169], v[160:161], v[166:167]
	v_mov_b32_e32 v163, v160
	v_mov_b32_e32 v165, v169
	v_pk_add_f32 v[170:171], v[162:163], v[164:165] neg_lo:[0,1] neg_hi:[0,1]
	v_pk_add_f32 v[162:163], v[162:163], v[164:165]
	v_mov_b32_e32 v166, v167
	v_pk_add_f32 v[164:165], v[162:163], v[160:161] op_sel:[1,0] op_sel_hi:[0,1] neg_lo:[0,1] neg_hi:[0,1]
	v_pk_add_f32 v[172:173], v[168:169], v[164:165] op_sel_hi:[1,0] neg_lo:[0,1] neg_hi:[0,1]
	v_mov_b32_e32 v168, v169
	v_mov_b32_e32 v169, v163
	v_pk_mov_b32 v[164:165], v[160:161], v[164:165] op_sel:[1,0]
	v_mov_b32_e32 v167, v160
	v_pk_add_f32 v[164:165], v[168:169], v[164:165] neg_lo:[0,1] neg_hi:[0,1]
	v_mov_b32_e32 v172, v170
	v_pk_add_f32 v[160:161], v[166:167], v[164:165] neg_lo:[0,1] neg_hi:[0,1]
	v_mov_b32_e32 v171, v163
	v_pk_add_f32 v[164:165], v[172:173], v[160:161]
	s_nop 0
	v_pk_add_f32 v[166:167], v[164:165], v[164:165] op_sel:[0,1] op_sel_hi:[1,0]
	s_nop 0
	v_pk_add_f32 v[162:163], v[162:163], v[166:167] op_sel:[1,0] op_sel_hi:[0,1]
	v_mov_b32_e32 v165, v162
	v_pk_add_f32 v[168:169], v[164:165], v[170:171] neg_lo:[0,1] neg_hi:[0,1]
	v_mov_b32_e32 v161, v166
	v_sub_f32_e32 v163, v164, v168
	v_pk_add_f32 v[160:161], v[160:161], v[168:169] neg_lo:[0,1] neg_hi:[0,1]
	v_sub_f32_e32 v163, v170, v163
	v_add_f32_e32 v160, v160, v163
	v_add_f32_e32 v160, v160, v161
	v_add_f32_e32 v160, v162, v160
	v_cndmask_b32_e32 v160, v198, v160, vcc
	v_cmp_lt_f32_e64 vcc, |v175|, s42
	s_nop 1
	v_cndmask_b32_e32 v160, v160, v175, vcc
	v_sub_f32_e32 v160, v174, v160
	global_store_dword v[180:181], v160, off
	s_branch .LBB0_36
